# opt17
# baseline (speedup 1.0000x reference)
; template <bool PASS2>
; __device__ __forceinline__ void ssm_block(const P& p, int blk) {
;     ...
;       const bf16x8 ua = ufr;
;       if (sc < 7) ufr = *(const bf16x8*)(proj + (size_t)((sc + 1) * 32 + l31) * 4096 + 1536 + g * 16 + hi * 8);
;       f32x16 d0, d1, d2, d3;
;       {
;         const f32x16 z = {0.f, 0.f, 0.f, 0.f, 0.f, 0.f, 0.f, 0.f, 0.f, 0.f, 0.f, 0.f, 0.f, 0.f, 0.f, 0.f};
;         d0 = __builtin_amdgcn_mfma_f32_32x32x16_bf16(ua, bbf[0], z, 0, 0, 0);
;         d1 = __builtin_amdgcn_mfma_f32_32x32x16_bf16(ua, bbf[1], z, 0, 0, 0);
;         d2 = __builtin_amdgcn_mfma_f32_32x32x16_bf16(ua, bbf[2], z, 0, 0, 0);
;         d3 = __builtin_amdgcn_mfma_f32_32x32x16_bf16(ua, bbf[3], z, 0, 0, 0);
;       }
; #pragma unroll
;       for (int r = 0; r < 16; ++r) {
;         auto s01 = __builtin_amdgcn_permlane32_swap(__float_as_uint(d0[r]), __float_as_uint(d1[r]), false, false);
;         d0[r] = __uint_as_float(s01[0]); d1[r] = __uint_as_float(s01[1]);
;         auto s23 = __builtin_amdgcn_permlane32_swap(__float_as_uint(d2[r]), __float_as_uint(d3[r]), false, false);
;         d2[r] = __uint_as_float(s23[0]); d3[r] = __uint_as_float(s23[1]);
;       }
; #pragma unroll
;       for (int t = 0; t < 32; ++t) {
;         const int r = (t & 3) + 4 * (t >> 3);
;         const float bur = ((t >> 2) & 1) ? d1[r] : d0[r];
;         const float bui = ((t >> 2) & 1) ? d3[r] : d2[r];
;         const float nr = lr * xr - li * xi + bur, ni = lr * xi + li * xr + bui;
;         xr = nr; xi = ni;
;         if (PASS2) { xs[t * XS_STRIDE + lane] = f2bf(xr); xs[t * XS_STRIDE + 64 + lane] = f2bf(xi); }
;       }
.LBB0_355:
	v_mov_b32_e32 v132, 0
	v_mov_b32_e32 v133, 0
	v_mov_b32_e32 v134, 0
	v_mov_b32_e32 v135, 0
	v_mov_b32_e32 v136, 0
	v_mov_b32_e32 v137, 0
	v_mov_b32_e32 v138, 0
	v_mov_b32_e32 v139, 0
	v_lshl_add_u64 v[140:141], v[114:115], 0, s[34:35]
	s_and_saveexec_b64 s[36:37], s[4:5]
	v_add_co_u32_e32 v142, vcc, 0xad00000, v140
	s_nop 1
	v_addc_co_u32_e32 v143, vcc, 0, v141, vcc
	global_load_dwordx4 v[132:135], v[142:143], off offset:3072
	v_add_co_u32_e32 v142, vcc, 0xad20000, v140
	s_nop 1
	v_addc_co_u32_e32 v143, vcc, 0, v141, vcc
	global_load_dwordx4 v[136:139], v[142:143], off offset:3072
	s_or_b64 exec, exec, s[36:37]
	v_mfma_f32_32x32x16_bf16 v[48:63], v[0:3], v[64:67], 0
	v_mul_f32_e32 v131, v119, v125
	v_fma_f32 v131, v118, v124, -v131
	v_mul_f32_e32 v125, v118, v125
	v_fmac_f32_e32 v125, v119, v124
	v_mfma_f32_32x32x16_bf16 v[16:31], v[0:3], v[68:71], 0
	v_mfma_f32_32x32x16_bf16 v[32:47], v[0:3], v[72:75], 0
	s_nop 10
	v_permlane32_swap_b32_e32 v48, v16
	v_add_f32_e32 v48, v131, v48
	v_cvt_pk_bf16_f32 v124, v48, s0
	ds_write_b16 v128, v124
	v_permlane32_swap_b32_e32 v49, v17
	v_mfma_f32_32x32x16_bf16 v[0:15], v[0:3], v[76:79], 0
	v_permlane32_swap_b32_e32 v50, v18
	v_permlane32_swap_b32_e32 v51, v19
	v_permlane32_swap_b32_e32 v52, v20
	v_permlane32_swap_b32_e32 v53, v21
	s_nop 7
	v_permlane32_swap_b32_e32 v32, v0
	v_add_f32_e32 v32, v125, v32
	v_cvt_pk_bf16_f32 v124, v32, s0
	ds_write_b16 v128, v124 offset:128
	v_mul_f32_e32 v124, v119, v32
	v_fma_f32 v124, v118, v48, -v124
	v_mul_f32_e32 v32, v118, v32
	v_permlane32_swap_b32_e32 v33, v1
	v_add_f32_e32 v49, v124, v49
	v_fmac_f32_e32 v32, v119, v48
	v_add_f32_e32 v32, v32, v33
	v_cvt_pk_bf16_f32 v33, v49, v32
	ds_write_b16 v128, v33 offset:272
	ds_write_b16_d16_hi v128, v33 offset:400
	v_mul_f32_e32 v33, v119, v32
	v_fma_f32 v33, v118, v49, -v33
	v_mul_f32_e32 v48, v119, v49
	v_permlane32_swap_b32_e32 v34, v2
	v_add_f32_e32 v33, v33, v50
	v_fmac_f32_e32 v48, v118, v32
	v_add_f32_e32 v32, v48, v34
	v_cvt_pk_bf16_f32 v34, v33, v32
	ds_write_b16 v128, v34 offset:544
	ds_write_b16_d16_hi v128, v34 offset:672
	v_mul_f32_e32 v34, v119, v32
	v_fma_f32 v34, v118, v33, -v34
	v_mul_f32_e32 v33, v119, v33
	v_permlane32_swap_b32_e32 v35, v3
	v_add_f32_e32 v34, v34, v51
	v_fmac_f32_e32 v33, v118, v32
	v_add_f32_e32 v32, v33, v35
	v_cvt_pk_bf16_f32 v33, v34, v32
	ds_write_b16 v128, v33 offset:816
	ds_write_b16_d16_hi v128, v33 offset:944
	v_mul_f32_e32 v33, v119, v32
	v_fma_f32 v33, v118, v34, -v33
	v_add_f32_e32 v16, v33, v16
	v_mul_f32_e32 v33, v119, v34
	v_fmac_f32_e32 v33, v118, v32
	v_add_f32_e32 v0, v33, v0
	v_cvt_pk_bf16_f32 v32, v16, v0
	ds_write_b16 v128, v32 offset:1088
	ds_write_b16_d16_hi v128, v32 offset:1216
	v_mul_f32_e32 v32, v119, v0
	v_fma_f32 v32, v118, v16, -v32
	v_mul_f32_e32 v16, v119, v16
	v_add_f32_e32 v17, v32, v17
	v_fmac_f32_e32 v16, v118, v0
	v_add_f32_e32 v0, v16, v1
	v_cvt_pk_bf16_f32 v1, v17, v0
	ds_write_b16 v128, v1 offset:1360
	ds_write_b16_d16_hi v128, v1 offset:1488
	v_mul_f32_e32 v1, v119, v0
	v_fma_f32 v1, v118, v17, -v1
	v_mul_f32_e32 v16, v119, v17
	v_add_f32_e32 v1, v1, v18
	v_fmac_f32_e32 v16, v118, v0
	v_add_f32_e32 v0, v16, v2
	v_cvt_pk_bf16_f32 v2, v1, v0
	ds_write_b16 v128, v2 offset:1632
	ds_write_b16_d16_hi v128, v2 offset:1760
	v_mul_f32_e32 v2, v119, v0
	v_fma_f32 v2, v118, v1, -v2
	v_mul_f32_e32 v1, v119, v1
	v_add_f32_e32 v2, v2, v19
	v_fmac_f32_e32 v1, v118, v0
	v_add_f32_e32 v0, v1, v3
	v_cvt_pk_bf16_f32 v1, v2, v0
	ds_write_b16 v128, v1 offset:1904
	ds_write_b16_d16_hi v128, v1 offset:2032
	v_mul_f32_e32 v1, v119, v0
	v_fma_f32 v1, v118, v2, -v1
	v_mul_f32_e32 v2, v119, v2
	v_permlane32_swap_b32_e32 v36, v4
	v_add_f32_e32 v1, v1, v52
	v_fmac_f32_e32 v2, v118, v0
	v_add_f32_e32 v0, v2, v36
	v_cvt_pk_bf16_f32 v2, v1, v0
	ds_write_b16 v128, v2 offset:2176
	ds_write_b16_d16_hi v128, v2 offset:2304
	v_mul_f32_e32 v2, v119, v0
	v_fma_f32 v2, v118, v1, -v2
	v_mul_f32_e32 v1, v119, v1
	v_permlane32_swap_b32_e32 v37, v5
	v_add_f32_e32 v2, v2, v53
	v_fmac_f32_e32 v1, v118, v0
	v_add_f32_e32 v0, v1, v37
	v_cvt_pk_bf16_f32 v1, v2, v0
	ds_write_b16 v128, v1 offset:2448
	ds_write_b16_d16_hi v128, v1 offset:2576
	v_mul_f32_e32 v1, v119, v0
	v_permlane32_swap_b32_e32 v54, v22
	v_fma_f32 v1, v118, v2, -v1
	v_mul_f32_e32 v2, v119, v2
	v_permlane32_swap_b32_e32 v38, v6
	v_add_f32_e32 v1, v1, v54
	v_fmac_f32_e32 v2, v118, v0
	v_add_f32_e32 v0, v2, v38
	v_cvt_pk_bf16_f32 v2, v1, v0
	ds_write_b16 v128, v2 offset:2720
	ds_write_b16_d16_hi v128, v2 offset:2848
	v_mul_f32_e32 v2, v119, v0
	v_permlane32_swap_b32_e32 v55, v23
	v_fma_f32 v2, v118, v1, -v2
	v_mul_f32_e32 v1, v119, v1
	v_permlane32_swap_b32_e32 v39, v7
	v_add_f32_e32 v2, v2, v55
	v_fmac_f32_e32 v1, v118, v0
	v_add_f32_e32 v0, v1, v39
	v_cvt_pk_bf16_f32 v1, v2, v0
	ds_write_b16 v128, v1 offset:2992
	ds_write_b16_d16_hi v128, v1 offset:3120
	v_mul_f32_e32 v1, v119, v0
	v_fma_f32 v1, v118, v2, -v1
	v_mul_f32_e32 v2, v119, v2
	v_add_f32_e32 v1, v1, v20
	v_fmac_f32_e32 v2, v118, v0
	v_add_f32_e32 v0, v2, v4
	v_cvt_pk_bf16_f32 v2, v1, v0
	ds_write_b16 v128, v2 offset:3264
	ds_write_b16_d16_hi v128, v2 offset:3392
	v_mul_f32_e32 v2, v119, v0
	v_fma_f32 v2, v118, v1, -v2
	v_mul_f32_e32 v1, v119, v1
	v_add_f32_e32 v2, v2, v21
	v_fmac_f32_e32 v1, v118, v0
	v_add_f32_e32 v0, v1, v5
	v_cvt_pk_bf16_f32 v1, v2, v0
	ds_write_b16 v128, v1 offset:3536
	ds_write_b16_d16_hi v128, v1 offset:3664
	v_mul_f32_e32 v1, v119, v0
	v_fma_f32 v1, v118, v2, -v1
	v_mul_f32_e32 v2, v119, v2
	v_add_f32_e32 v1, v1, v22
	v_fmac_f32_e32 v2, v118, v0
	v_add_f32_e32 v0, v2, v6
	v_cvt_pk_bf16_f32 v2, v1, v0
	ds_write_b16 v128, v2 offset:3808
; template <bool PASS2>
; __device__ __forceinline__ void ssm_block(const P& p, int blk) {
;     ...
;       for (int t = 0; t < 32; ++t) {
;         const int r = (t & 3) + 4 * (t >> 3);
;         const float bur = ((t >> 2) & 1) ? d1[r] : d0[r];
;         const float bui = ((t >> 2) & 1) ? d3[r] : d2[r];
;         const float nr = lr * xr - li * xi + bur, ni = lr * xi + li * xr + bui;
;         xr = nr; xi = ni;
;         if (PASS2) { xs[t * XS_STRIDE + lane] = f2bf(xr); xs[t * XS_STRIDE + 64 + lane] = f2bf(xi); }
;       }
;     ...
; #pragma unroll
;         for (int rt = 0; rt < 2; ++rt) {
;           f32x4 acc = f32x4{0.f, 0.f, 0.f, 0.f};
; #pragma unroll
;           for (int kk = 0; kk < 4; ++kk) {
;             bf16x8 af = *(const bf16x8*)(xs + (rt * 16 + l15) * XS_STRIDE + kk * 32 + q4 * 8);
	ds_write_b16_d16_hi v128, v2 offset:3936
	v_mul_f32_e32 v2, v119, v0
	v_fma_f32 v2, v118, v1, -v2
	v_mul_f32_e32 v1, v119, v1
	v_add_f32_e32 v2, v2, v23
	v_fmac_f32_e32 v1, v118, v0
	v_add_f32_e32 v0, v1, v7
	v_cvt_pk_bf16_f32 v1, v2, v0
	ds_write_b16 v128, v1 offset:4080
	ds_write_b16_d16_hi v128, v1 offset:4208
	v_mul_f32_e32 v1, v119, v0
	v_permlane32_swap_b32_e32 v56, v24
	v_fma_f32 v1, v118, v2, -v1
	v_mul_f32_e32 v2, v119, v2
	v_permlane32_swap_b32_e32 v40, v8
	v_add_f32_e32 v1, v1, v56
	v_fmac_f32_e32 v2, v118, v0
	v_add_f32_e32 v0, v2, v40
	v_cvt_pk_bf16_f32 v2, v1, v0
	ds_write_b16 v128, v2 offset:4352
	ds_write_b16_d16_hi v128, v2 offset:4480
	v_mul_f32_e32 v2, v119, v0
	v_permlane32_swap_b32_e32 v57, v25
	v_fma_f32 v2, v118, v1, -v2
	v_mul_f32_e32 v1, v119, v1
	v_permlane32_swap_b32_e32 v41, v9
	v_add_f32_e32 v2, v2, v57
	v_fmac_f32_e32 v1, v118, v0
	v_add_f32_e32 v0, v1, v41
	v_cvt_pk_bf16_f32 v1, v2, v0
	ds_write_b16 v128, v1 offset:4624
	ds_write_b16_d16_hi v128, v1 offset:4752
	v_mul_f32_e32 v1, v119, v0
	v_permlane32_swap_b32_e32 v58, v26
	v_fma_f32 v1, v118, v2, -v1
	v_mul_f32_e32 v2, v119, v2
	v_permlane32_swap_b32_e32 v42, v10
	v_add_f32_e32 v1, v1, v58
	v_fmac_f32_e32 v2, v118, v0
	v_add_f32_e32 v0, v2, v42
	v_cvt_pk_bf16_f32 v2, v1, v0
	ds_write_b16 v128, v2 offset:4896
	ds_write_b16_d16_hi v128, v2 offset:5024
	v_mul_f32_e32 v2, v119, v0
	v_permlane32_swap_b32_e32 v59, v27
	v_fma_f32 v2, v118, v1, -v2
	v_mul_f32_e32 v1, v119, v1
	v_permlane32_swap_b32_e32 v43, v11
	v_add_f32_e32 v2, v2, v59
	v_fmac_f32_e32 v1, v118, v0
	v_add_f32_e32 v0, v1, v43
	v_cvt_pk_bf16_f32 v1, v2, v0
	ds_write_b16 v128, v1 offset:5168
	ds_write_b16_d16_hi v128, v1 offset:5296
	v_mul_f32_e32 v1, v119, v0
	v_fma_f32 v1, v118, v2, -v1
	v_mul_f32_e32 v2, v119, v2
	v_add_f32_e32 v1, v1, v24
	v_fmac_f32_e32 v2, v118, v0
	v_add_f32_e32 v0, v2, v8
	v_cvt_pk_bf16_f32 v2, v1, v0
	ds_write_b16 v128, v2 offset:5440
	ds_write_b16_d16_hi v128, v2 offset:5568
	v_mul_f32_e32 v2, v119, v0
	v_fma_f32 v2, v118, v1, -v2
	v_mul_f32_e32 v1, v119, v1
	v_add_f32_e32 v2, v2, v25
	v_fmac_f32_e32 v1, v118, v0
	v_add_f32_e32 v0, v1, v9
	v_cvt_pk_bf16_f32 v1, v2, v0
	ds_write_b16 v128, v1 offset:5712
	ds_write_b16_d16_hi v128, v1 offset:5840
	v_mul_f32_e32 v1, v119, v0
	v_fma_f32 v1, v118, v2, -v1
	v_mul_f32_e32 v2, v119, v2
	v_add_f32_e32 v1, v1, v26
	v_fmac_f32_e32 v2, v118, v0
	v_add_f32_e32 v0, v2, v10
	v_cvt_pk_bf16_f32 v2, v1, v0
	ds_write_b16 v128, v2 offset:5984
	ds_write_b16_d16_hi v128, v2 offset:6112
	v_mul_f32_e32 v2, v119, v0
	v_fma_f32 v2, v118, v1, -v2
	v_mul_f32_e32 v1, v119, v1
	v_add_f32_e32 v2, v2, v27
	v_fmac_f32_e32 v1, v118, v0
	v_add_f32_e32 v0, v1, v11
	v_cvt_pk_bf16_f32 v1, v2, v0
	ds_write_b16 v128, v1 offset:6256
	ds_write_b16_d16_hi v128, v1 offset:6384
	v_mul_f32_e32 v1, v119, v0
	v_permlane32_swap_b32_e32 v60, v28
	v_fma_f32 v1, v118, v2, -v1
	v_mul_f32_e32 v2, v119, v2
	v_permlane32_swap_b32_e32 v44, v12
	v_add_f32_e32 v1, v1, v60
	v_fmac_f32_e32 v2, v118, v0
	v_add_f32_e32 v0, v2, v44
	v_cvt_pk_bf16_f32 v2, v1, v0
	ds_write_b16 v128, v2 offset:6528
	ds_write_b16_d16_hi v128, v2 offset:6656
	v_mul_f32_e32 v2, v119, v0
	v_permlane32_swap_b32_e32 v61, v29
	v_fma_f32 v2, v118, v1, -v2
	v_mul_f32_e32 v1, v119, v1
	v_permlane32_swap_b32_e32 v45, v13
	v_add_f32_e32 v2, v2, v61
	v_fmac_f32_e32 v1, v118, v0
	v_add_f32_e32 v0, v1, v45
	v_cvt_pk_bf16_f32 v1, v2, v0
	ds_write_b16 v128, v1 offset:6800
	ds_write_b16_d16_hi v128, v1 offset:6928
	v_mul_f32_e32 v1, v119, v0
	v_permlane32_swap_b32_e32 v62, v30
	v_fma_f32 v1, v118, v2, -v1
	v_mul_f32_e32 v2, v119, v2
	v_permlane32_swap_b32_e32 v46, v14
	v_add_f32_e32 v1, v1, v62
	v_fmac_f32_e32 v2, v118, v0
	v_add_f32_e32 v0, v2, v46
	v_cvt_pk_bf16_f32 v2, v1, v0
	ds_write_b16 v128, v2 offset:7072
	ds_write_b16_d16_hi v128, v2 offset:7200
	v_mul_f32_e32 v2, v119, v0
	v_permlane32_swap_b32_e32 v63, v31
	v_fma_f32 v2, v118, v1, -v2
	v_mul_f32_e32 v1, v119, v1
	v_permlane32_swap_b32_e32 v47, v15
	v_add_f32_e32 v2, v2, v63
	v_fmac_f32_e32 v1, v118, v0
	v_add_f32_e32 v3, v1, v47
	v_cvt_pk_bf16_f32 v0, v2, v3
	ds_write_b16 v128, v0 offset:7344
	ds_write_b16_d16_hi v128, v0 offset:7472
	v_mul_f32_e32 v0, v119, v3
	v_mul_f32_e32 v1, v119, v2
	v_fma_f32 v0, v118, v2, -v0
	v_fmac_f32_e32 v1, v118, v3
	v_mov_b32_e32 v2, v28
	v_mov_b32_e32 v3, v12
	v_pk_add_f32 v[0:1], v[0:1], v[2:3]
	v_mov_b32_e32 v12, v29
	v_cvt_pk_bf16_f32 v2, v0, s0
	ds_write_b16 v128, v2 offset:7616
	v_cvt_pk_bf16_f32 v2, v1, s0
	ds_write_b16 v128, v2 offset:7744
	v_pk_mul_f32 v[2:3], v[122:123], v[0:1]
	v_mov_b32_e32 v4, v30
	v_pk_fma_f32 v[6:7], v[120:121], v[0:1], v[2:3] op_sel:[0,0,1] op_sel_hi:[1,1,0] neg_lo:[0,0,1] neg_hi:[0,0,1]
	v_pk_fma_f32 v[0:1], v[120:121], v[0:1], v[2:3] op_sel:[0,0,1] op_sel_hi:[1,1,0]
	v_mov_b32_e32 v5, v14
	v_mov_b32_e32 v7, v1
	v_pk_add_f32 v[0:1], v[6:7], v[12:13]
	v_mov_b32_e32 v14, v31
	v_cvt_pk_bf16_f32 v2, v0, s0
	ds_write_b16 v128, v2 offset:7888
	v_cvt_pk_bf16_f32 v2, v1, s0
	ds_write_b16 v128, v2 offset:8016
	v_pk_mul_f32 v[2:3], v[122:123], v[0:1]
	s_nop 0
	v_pk_fma_f32 v[6:7], v[120:121], v[0:1], v[2:3] op_sel:[0,0,1] op_sel_hi:[1,1,0] neg_lo:[0,0,1] neg_hi:[0,0,1]
	v_pk_fma_f32 v[0:1], v[120:121], v[0:1], v[2:3] op_sel:[0,0,1] op_sel_hi:[1,1,0]
	s_nop 0
	v_mov_b32_e32 v7, v1
	v_pk_add_f32 v[0:1], v[6:7], v[4:5]
	s_nop 0
	v_cvt_pk_bf16_f32 v2, v0, s0
	ds_write_b16 v128, v2 offset:8160
	v_cvt_pk_bf16_f32 v2, v1, s0
	ds_write_b16 v128, v2 offset:8288
	v_pk_mul_f32 v[2:3], v[122:123], v[0:1]
	s_nop 0
	v_pk_fma_f32 v[4:5], v[120:121], v[0:1], v[2:3] op_sel:[0,0,1] op_sel_hi:[1,1,0] neg_lo:[0,0,1] neg_hi:[0,0,1]
	v_pk_fma_f32 v[0:1], v[120:121], v[0:1], v[2:3] op_sel:[0,0,1] op_sel_hi:[1,1,0]
	s_nop 0
	v_mov_b32_e32 v5, v1
	v_pk_add_f32 v[124:125], v[4:5], v[14:15]
	s_nop 0
	v_cvt_pk_bf16_f32 v0, v124, s0
	ds_write_b16 v128, v0 offset:8432
	v_cvt_pk_bf16_f32 v0, v125, s0
	ds_write_b16 v128, v0 offset:8560
	ds_read_b128 v[0:3], v130
	ds_read_b128 v[4:7], v130 offset:64
	s_waitcnt lgkmcnt(1)
; __device__ __forceinline__ float sigm(float x) { return __builtin_amdgcn_rcpf(1.f + __expf(-x)); }
; template <bool PASS2>
; __device__ __forceinline__ void ssm_block(const P& p, int blk) {
;     ...
; #pragma unroll
;         for (int rt = 0; rt < 2; ++rt) {
;           f32x4 acc = f32x4{0.f, 0.f, 0.f, 0.f};
; #pragma unroll
;           for (int kk = 0; kk < 4; ++kk) {
;             bf16x8 af = *(const bf16x8*)(xs + (rt * 16 + l15) * XS_STRIDE + kk * 32 + q4 * 8);
;             acc = __builtin_amdgcn_mfma_f32_16x16x32_bf16(af, cf[kk], acc, 0, 0, 0);
;           }
;           {
;             bf16x8 au = {0, 0, 0, 0, 0, 0, 0, 0};
;             if (q4 < 2) au = *(const bf16x8*)(proj + (size_t)(sc * 32 + rt * 16 + l15) * 4096 + 1536 + g * 16 + q4 * 8);
;             acc = __builtin_amdgcn_mfma_f32_16x16x32_bf16(au, df, acc, 0, 0, 0);
;           }
; #pragma unroll
;           for (int r = 0; r < 4; ++r) {
;             const int t = rt * 16 + q4 * 4 + r;
;             const float y = acc[r];
;             const float ge = y * sigm(1.5957691216057308f * (y + 0.044715f * y * y * y));
;             proj[(size_t)(sc * 32 + t) * 4096 + 1536 + g * 16 + l15] = f2bf(ge);
;           }
;         }
	v_mfma_f32_16x16x32_bf16 v[0:3], v[0:3], v[80:83], 0
	ds_read_b128 v[8:11], v130 offset:128
	s_waitcnt lgkmcnt(1)
	v_mfma_f32_16x16x32_bf16 v[0:3], v[4:7], v[84:87], v[0:3]
	ds_read_b128 v[4:7], v130 offset:192
	s_waitcnt vmcnt(1) lgkmcnt(1)
	v_mfma_f32_16x16x32_bf16 v[0:3], v[8:11], v[88:91], v[0:3]
	v_lshl_add_u64 v[10:11], v[114:115], 0, s[34:35]
	v_mov_b32_e32 v8, 0
	v_mov_b32_e32 v9, 0
	s_waitcnt vmcnt(0) lgkmcnt(0)
	v_mfma_f32_16x16x32_bf16 v[2:5], v[4:7], v[92:95], v[0:3]
	v_mov_b32_e32 v6, 0
	v_mov_b32_e32 v7, 0
	s_nop 0
	v_mov_b32_e32 v0, 0
	v_mfma_f32_16x16x32_bf16 v[2:5], v[132:135], v[96:99], v[2:5]
	v_lshl_add_u64 v[8:9], v[112:113], 0, s[34:35]
	ds_read_b128 v[20:23], v130 offset:4480
	ds_read_b128 v[16:19], v130 offset:4416
	s_nop 4
	v_mul_f32_e32 v1, 0x3d372713, v2
	v_mul_f32_e32 v1, v2, v1
	v_fma_f32 v1, v2, v1, v2
	v_mul_f32_e32 v1, 0x3fcc422a, v1
	v_mul_f32_e32 v1, 0xbfb8aa3b, v1
	v_mul_f32_e32 v6, 0x3d372713, v3
	v_exp_f32_e32 v1, v1
	v_mul_f32_e32 v6, v3, v6
	v_fma_f32 v6, v3, v6, v3
	v_mul_f32_e32 v6, 0x3fcc422a, v6
	v_mul_f32_e32 v6, 0xbfb8aa3b, v6
	v_add_f32_e32 v1, 1.0, v1
	v_exp_f32_e32 v6, v6
	v_rcp_f32_e32 v1, v1
	v_add_f32_e32 v6, 1.0, v6
	v_mul_f32_e32 v1, v2, v1
	v_mul_f32_e32 v2, 0x3d372713, v4
	v_rcp_f32_e32 v12, v6
	v_mul_f32_e32 v2, v4, v2
	v_add_co_u32_e32 v6, vcc, s38, v8
	v_fma_f32 v2, v4, v2, v4
	v_cvt_pk_bf16_f32 v1, v1, s0
	v_addc_co_u32_e32 v7, vcc, 0, v9, vcc
	v_mul_f32_e32 v2, 0x3fcc422a, v2
	global_store_short v[6:7], v1, off offset:3072
	v_mul_f32_e32 v2, 0xbfb8aa3b, v2
	v_mul_f32_e32 v7, 0x3d372713, v5
	v_mul_f32_e32 v1, v3, v12
	v_exp_f32_e32 v6, v2
	v_mul_f32_e32 v7, v5, v7
	ds_read_b128 v[12:15], v130 offset:4352
	v_fma_f32 v7, v5, v7, v5
	v_mul_f32_e32 v7, 0x3fcc422a, v7
	v_mul_f32_e32 v7, 0xbfb8aa3b, v7
	v_add_f32_e32 v6, 1.0, v6
	v_exp_f32_e32 v7, v7
	v_rcp_f32_e32 v6, v6
	v_add_co_u32_e32 v2, vcc, s39, v8
	v_cvt_pk_bf16_f32 v1, v1, s0
	s_nop 0
	v_addc_co_u32_e32 v3, vcc, 0, v9, vcc
	global_store_short v[2:3], v1, off offset:3072
	v_add_f32_e32 v2, 1.0, v7
	v_mul_f32_e32 v1, v4, v6
	v_rcp_f32_e32 v4, v2
	s_waitcnt lgkmcnt(0)
	v_mfma_f32_16x16x32_bf16 v[12:15], v[12:15], v[80:83], 0
	v_add_co_u32_e32 v2, vcc, s40, v8
	v_cvt_pk_bf16_f32 v1, v1, s0
	s_nop 0
	v_addc_co_u32_e32 v3, vcc, 0, v9, vcc
	global_store_short v[2:3], v1, off offset:3072
	v_mul_f32_e32 v1, v5, v4
	v_mfma_f32_16x16x32_bf16 v[2:5], v[16:19], v[84:87], v[12:15]
	v_add_co_u32_e32 v6, vcc, s41, v8
	v_cvt_pk_bf16_f32 v1, v1, s0
	s_nop 0
	ds_read_b128 v[12:15], v130 offset:4544
	v_mfma_f32_16x16x32_bf16 v[2:5], v[20:23], v[88:91], v[2:5]
	v_addc_co_u32_e32 v7, vcc, 0, v9, vcc
	global_store_short v[6:7], v1, off offset:3072
	s_waitcnt lgkmcnt(0)
	v_mfma_f32_16x16x32_bf16 v[4:7], v[12:15], v[92:95], v[2:5]
	v_mov_b32_e32 v1, 0
	s_nop 2
	v_mov_b32_e32 v2, 0
	v_mov_b32_e32 v3, 0
	s_branch .LBB0_352
